# grid barrier: all workgroups wait on the top-level arrival counter reaching (gen+1)*n_xcd; generation word no longer bumped (one release hop less)
# baseline (speedup 1.0000x reference)
; __device__ __forceinline__ unsigned xb_ld(unsigned* p)              { return __hip_atomic_load(p, __ATOMIC_RELAXED, __HIP_MEMORY_SCOPE_AGENT); }
; __device__ __forceinline__ unsigned xb_add(unsigned* p, unsigned v) { return __hip_atomic_fetch_add(p, v, __ATOMIC_RELAXED, __HIP_MEMORY_SCOPE_AGENT); }
; #define XB_SPIN(cond, bar) do { unsigned _sp = 0; while (cond) { __builtin_amdgcn_s_sleep(1); \
;     if ((++_sp & 255u) == 0u) { if (xb_ld(&(bar)[XB_TMO])) break; if (_sp > XB_SPIN_CAP) { atomicAdd(&(bar)[XB_TMO], 1u); break; } } } } while (0)
; __device__ __forceinline__ void xcd_barrier(const XcdBarrier& b) {
;     ...
;         const unsigned old = xb_add(&bar[XB_XSUB(b.x)], 1u);
;         const unsigned gen = old / nloc;
;         if (old + 1u == (gen + 1u) * nloc) {
;             __builtin_amdgcn_fence(__ATOMIC_RELEASE, "agent");
;             asm volatile("s_waitcnt vmcnt(0)" ::: "memory");
;             const unsigned og = xb_add(&bar[XB_TOP], 1u);
;             const unsigned tg = og / nx;
;             if (og + 1u == (tg + 1u) * nx) xb_add(&bar[XB_TOPGEN], 1u);
;             else XB_SPIN(xb_ld(&bar[XB_TOPGEN]) == tg, bar);
;             __builtin_amdgcn_fence(__ATOMIC_ACQUIRE, "agent");
;             xb_add(&bar[XB_XGEN(b.x)], 1u);
;             asm volatile("s_waitcnt vmcnt(0)" ::: "memory");
;         } else {
;             XB_SPIN(xb_ld(&bar[XB_XGEN(b.x)]) == gen, bar);
.LBB0_120:
	s_or_b64 exec, exec, s[12:13]
	v_cvt_f32_u32_e32 v4, v2
	s_waitcnt vmcnt(0)
	v_readfirstlane_b32 s3, v3
	v_sub_u32_e32 v3, 0, v2
	v_rcp_iflag_f32_e32 v4, v4
	v_add_u32_e32 v5, s3, v1
	v_mul_f32_e32 v4, 0x4f7ffffe, v4
	v_cvt_u32_f32_e32 v4, v4
	v_mul_lo_u32 v1, v3, v4
	v_mul_hi_u32 v1, v4, v1
	v_add_u32_e32 v1, v4, v1
	v_mul_hi_u32 v1, v5, v1
	v_mul_lo_u32 v3, v1, v2
	v_sub_u32_e32 v3, v5, v3
	v_add_u32_e32 v4, 1, v1
	v_cmp_ge_u32_e32 vcc, v3, v2
	s_nop 1
	v_cndmask_b32_e32 v1, v1, v4, vcc
	v_sub_u32_e32 v4, v3, v2
	v_cndmask_b32_e32 v3, v3, v4, vcc
	v_add_u32_e32 v4, 1, v1
	v_cmp_ge_u32_e32 vcc, v3, v2
	v_add_u32_e32 v3, 1, v5
	s_nop 0
	v_cndmask_b32_e32 v1, v1, v4, vcc
	v_mul_lo_u32 v4, v2, v1
	v_add_u32_e32 v2, v4, v2
	v_cmp_ne_u32_e32 vcc, v3, v2
	s_and_saveexec_b64 s[10:11], vcc
	s_xor_b64 s[10:11], exec, s[10:11]
	s_cbranch_execz .LBB0_134
	s_waitcnt lgkmcnt(0)
	v_add_u32_e32 v16, 1, v1
	v_mul_lo_u32 v16, v16, v0
	v_mov_b32_e32 v0, 0
	s_add_u32 s16, s6, 0x2e803400
	s_addc_u32 s17, s7, 0
	global_load_dword v0, v0, s[16:17] sc1
	s_waitcnt vmcnt(0)
	v_cmp_lt_u32_e32 vcc, v0, v16
	s_and_saveexec_b64 s[12:13], vcc
	s_cbranch_execz .LBB0_133
	s_add_u32 s14, s6, 0x2e800200
	s_addc_u32 s15, s7, 0
	s_mov_b32 s3, 1
	s_mov_b64 s[18:19], 0
	v_mov_b32_e32 v0, 0
	s_branch .LBB0_124

; __device__ __forceinline__ unsigned xb_ld(unsigned* p)              { return __hip_atomic_load(p, __ATOMIC_RELAXED, __HIP_MEMORY_SCOPE_AGENT); }
; __device__ __forceinline__ unsigned xb_add(unsigned* p, unsigned v) { return __hip_atomic_fetch_add(p, v, __ATOMIC_RELAXED, __HIP_MEMORY_SCOPE_AGENT); }
; #define XB_SPIN(cond, bar) do { unsigned _sp = 0; while (cond) { __builtin_amdgcn_s_sleep(1); \
;     if ((++_sp & 255u) == 0u) { if (xb_ld(&(bar)[XB_TMO])) break; if (_sp > XB_SPIN_CAP) { atomicAdd(&(bar)[XB_TMO], 1u); break; } } } } while (0)
; __device__ __forceinline__ void xcd_barrier(const XcdBarrier& b) {
;     ...
;             else XB_SPIN(xb_ld(&bar[XB_TOPGEN]) == tg, bar);
;             __builtin_amdgcn_fence(__ATOMIC_ACQUIRE, "agent");
;             xb_add(&bar[XB_XGEN(b.x)], 1u);
;             asm volatile("s_waitcnt vmcnt(0)" ::: "memory");
;         } else {
;             XB_SPIN(xb_ld(&bar[XB_XGEN(b.x)]) == gen, bar);
.LBB0_128:
	global_load_dword v2, v0, s[16:17] sc1
	s_add_i32 s3, s3, 1
	s_mov_b64 s[28:29], -1
	s_waitcnt vmcnt(0)
	v_cmp_ge_u32_e32 vcc, v2, v16
	s_orn2_b64 s[26:27], vcc, exec
	s_branch .LBB0_123

; __device__ __forceinline__ unsigned xb_ld(unsigned* p)              { return __hip_atomic_load(p, __ATOMIC_RELAXED, __HIP_MEMORY_SCOPE_AGENT); }
; __device__ __forceinline__ unsigned xb_add(unsigned* p, unsigned v) { return __hip_atomic_fetch_add(p, v, __ATOMIC_RELAXED, __HIP_MEMORY_SCOPE_AGENT); }
; #define XB_SPIN(cond, bar) do { unsigned _sp = 0; while (cond) { __builtin_amdgcn_s_sleep(1); \
;     if ((++_sp & 255u) == 0u) { if (xb_ld(&(bar)[XB_TMO])) break; if (_sp > XB_SPIN_CAP) { atomicAdd(&(bar)[XB_TMO], 1u); break; } } } } while (0)
; __device__ __forceinline__ void xcd_barrier(const XcdBarrier& b) {
;     ...
;             const unsigned og = xb_add(&bar[XB_TOP], 1u);
;             const unsigned tg = og / nx;
;             if (og + 1u == (tg + 1u) * nx) xb_add(&bar[XB_TOPGEN], 1u);
;             else XB_SPIN(xb_ld(&bar[XB_TOPGEN]) == tg, bar);
.LBB0_137:
	s_or_b64 exec, exec, s[12:13]
	v_cvt_f32_u32_e32 v3, v0
	s_waitcnt vmcnt(0)
	v_readfirstlane_b32 s3, v2
	s_add_u32 s12, s6, 0x2e803500
	s_addc_u32 s13, s7, 0
	v_rcp_iflag_f32_e32 v3, v3
	v_add_u32_e32 v1, s3, v1
	v_add_u32_e32 v4, 1, v1
	s_mov_b64 s[14:15], 0
	v_mul_f32_e32 v2, 0x4f7ffffe, v3
	v_cvt_u32_f32_e32 v2, v2
	v_sub_u32_e32 v3, 0, v0
	v_mul_lo_u32 v3, v3, v2
	v_mul_hi_u32 v3, v2, v3
	v_add_u32_e32 v2, v2, v3
	v_mul_hi_u32 v2, v1, v2
	v_mul_lo_u32 v3, v2, v0
	v_sub_u32_e32 v1, v1, v3
	v_add_u32_e32 v5, 1, v2
	v_cmp_ge_u32_e32 vcc, v1, v0
	v_sub_u32_e32 v3, v1, v0
	s_nop 0
	v_cndmask_b32_e32 v2, v2, v5, vcc
	v_cndmask_b32_e32 v1, v1, v3, vcc
	v_add_u32_e32 v3, 1, v2
	v_cmp_ge_u32_e32 vcc, v1, v0
	s_nop 1
	v_cndmask_b32_e32 v2, v2, v3, vcc
	v_mul_lo_u32 v1, v0, v2
	v_add_u32_e32 v0, v1, v0
	v_mov_b32_e32 v16, v0
	v_cmp_ne_u32_e32 vcc, v4, v0
	v_mov_b64_e32 v[0:1], s[12:13]
	s_and_saveexec_b64 s[10:11], vcc
	s_cbranch_execz .LBB0_149
	v_mov_b32_e32 v0, 0
	global_load_dword v1, v0, s[12:13] offset:-256 sc1
	s_mov_b64 s[18:19], 0
	s_waitcnt vmcnt(0)
	v_cmp_lt_u32_e32 vcc, v1, v16
	s_and_saveexec_b64 s[16:17], vcc
	s_cbranch_execz .LBB0_148
	s_add_u32 s14, s6, 0x2e800200
	s_addc_u32 s15, s7, 0
	s_mov_b32 s3, 1
	s_mov_b64 s[6:7], 0
	s_branch .LBB0_141

; __device__ __forceinline__ unsigned xb_ld(unsigned* p)              { return __hip_atomic_load(p, __ATOMIC_RELAXED, __HIP_MEMORY_SCOPE_AGENT); }
; __device__ __forceinline__ unsigned xb_add(unsigned* p, unsigned v) { return __hip_atomic_fetch_add(p, v, __ATOMIC_RELAXED, __HIP_MEMORY_SCOPE_AGENT); }
; #define XB_SPIN(cond, bar) do { unsigned _sp = 0; while (cond) { __builtin_amdgcn_s_sleep(1); \
;     if ((++_sp & 255u) == 0u) { if (xb_ld(&(bar)[XB_TMO])) break; if (_sp > XB_SPIN_CAP) { atomicAdd(&(bar)[XB_TMO], 1u); break; } } } } while (0)
; __device__ __forceinline__ void xcd_barrier(const XcdBarrier& b) {
;     ...
;             else XB_SPIN(xb_ld(&bar[XB_TOPGEN]) == tg, bar);
;             __builtin_amdgcn_fence(__ATOMIC_ACQUIRE, "agent");
;             xb_add(&bar[XB_XGEN(b.x)], 1u);
;             asm volatile("s_waitcnt vmcnt(0)" ::: "memory");
;         } else {
;             XB_SPIN(xb_ld(&bar[XB_XGEN(b.x)]) == gen, bar);
.LBB0_145:
	global_load_dword v1, v0, s[12:13] offset:-256 sc1
	s_add_i32 s3, s3, 1
	s_mov_b64 s[24:25], -1
	s_waitcnt vmcnt(0)
	v_cmp_ge_u32_e32 vcc, v1, v16
	s_orn2_b64 s[28:29], vcc, exec
	s_branch .LBB0_140

; __device__ __forceinline__ unsigned xb_ld(unsigned* p)              { return __hip_atomic_load(p, __ATOMIC_RELAXED, __HIP_MEMORY_SCOPE_AGENT); }
; __device__ __forceinline__ unsigned xb_add(unsigned* p, unsigned v) { return __hip_atomic_fetch_add(p, v, __ATOMIC_RELAXED, __HIP_MEMORY_SCOPE_AGENT); }
; #define XB_SPIN(cond, bar) do { unsigned _sp = 0; while (cond) { __builtin_amdgcn_s_sleep(1); \
;     if ((++_sp & 255u) == 0u) { if (xb_ld(&(bar)[XB_TMO])) break; if (_sp > XB_SPIN_CAP) { atomicAdd(&(bar)[XB_TMO], 1u); break; } } } } while (0)
; __device__ __forceinline__ void xcd_barrier(const XcdBarrier& b) {
;     ...
;         const unsigned old = xb_add(&bar[XB_XSUB(b.x)], 1u);
;         const unsigned gen = old / nloc;
;         if (old + 1u == (gen + 1u) * nloc) {
;             __builtin_amdgcn_fence(__ATOMIC_RELEASE, "agent");
;             asm volatile("s_waitcnt vmcnt(0)" ::: "memory");
;             const unsigned og = xb_add(&bar[XB_TOP], 1u);
;             const unsigned tg = og / nx;
;             if (og + 1u == (tg + 1u) * nx) xb_add(&bar[XB_TOPGEN], 1u);
;             else XB_SPIN(xb_ld(&bar[XB_TOPGEN]) == tg, bar);
;             __builtin_amdgcn_fence(__ATOMIC_ACQUIRE, "agent");
;             xb_add(&bar[XB_XGEN(b.x)], 1u);
;             asm volatile("s_waitcnt vmcnt(0)" ::: "memory");
;         } else {
;             XB_SPIN(xb_ld(&bar[XB_XGEN(b.x)]) == gen, bar);
.LBB0_206:
	s_or_b64 exec, exec, s[12:13]
	v_cvt_f32_u32_e32 v4, v2
	s_waitcnt vmcnt(0)
	v_readfirstlane_b32 s3, v3
	v_sub_u32_e32 v3, 0, v2
	v_rcp_iflag_f32_e32 v4, v4
	v_add_u32_e32 v5, s3, v1
	v_mul_f32_e32 v4, 0x4f7ffffe, v4
	v_cvt_u32_f32_e32 v4, v4
	v_mul_lo_u32 v1, v3, v4
	v_mul_hi_u32 v1, v4, v1
	v_add_u32_e32 v1, v4, v1
	v_mul_hi_u32 v1, v5, v1
	v_mul_lo_u32 v3, v1, v2
	v_sub_u32_e32 v3, v5, v3
	v_add_u32_e32 v4, 1, v1
	v_cmp_ge_u32_e32 vcc, v3, v2
	s_nop 1
	v_cndmask_b32_e32 v1, v1, v4, vcc
	v_sub_u32_e32 v4, v3, v2
	v_cndmask_b32_e32 v3, v3, v4, vcc
	v_add_u32_e32 v4, 1, v1
	v_cmp_ge_u32_e32 vcc, v3, v2
	v_add_u32_e32 v3, 1, v5
	s_nop 0
	v_cndmask_b32_e32 v1, v1, v4, vcc
	v_mul_lo_u32 v4, v2, v1
	v_add_u32_e32 v2, v4, v2
	v_cmp_ne_u32_e32 vcc, v3, v2
	s_and_saveexec_b64 s[10:11], vcc
	s_xor_b64 s[10:11], exec, s[10:11]
	s_cbranch_execz .LBB0_220
	s_waitcnt lgkmcnt(0)
	v_add_u32_e32 v16, 1, v1
	v_mul_lo_u32 v16, v16, v0
	s_add_u32 s16, s6, 0x2e803400
	s_addc_u32 s17, s7, 0
	global_load_dword v0, v97, s[16:17] sc1
	s_waitcnt vmcnt(0)
	v_cmp_lt_u32_e32 vcc, v0, v16
	s_and_saveexec_b64 s[12:13], vcc
	s_cbranch_execz .LBB0_219
	s_add_u32 s14, s6, 0x2e800200
	s_addc_u32 s15, s7, 0
	s_mov_b32 s3, 1
	s_mov_b64 s[34:35], 0
	s_branch .LBB0_210

; __device__ __forceinline__ unsigned xb_ld(unsigned* p)              { return __hip_atomic_load(p, __ATOMIC_RELAXED, __HIP_MEMORY_SCOPE_AGENT); }
; __device__ __forceinline__ unsigned xb_add(unsigned* p, unsigned v) { return __hip_atomic_fetch_add(p, v, __ATOMIC_RELAXED, __HIP_MEMORY_SCOPE_AGENT); }
; #define XB_SPIN(cond, bar) do { unsigned _sp = 0; while (cond) { __builtin_amdgcn_s_sleep(1); \
;     if ((++_sp & 255u) == 0u) { if (xb_ld(&(bar)[XB_TMO])) break; if (_sp > XB_SPIN_CAP) { atomicAdd(&(bar)[XB_TMO], 1u); break; } } } } while (0)
; __device__ __forceinline__ void xcd_barrier(const XcdBarrier& b) {
;     ...
;             else XB_SPIN(xb_ld(&bar[XB_TOPGEN]) == tg, bar);
;             __builtin_amdgcn_fence(__ATOMIC_ACQUIRE, "agent");
;             xb_add(&bar[XB_XGEN(b.x)], 1u);
;             asm volatile("s_waitcnt vmcnt(0)" ::: "memory");
;         } else {
;             XB_SPIN(xb_ld(&bar[XB_XGEN(b.x)]) == gen, bar);
.LBB0_214:
	global_load_dword v0, v97, s[16:17] sc1
	s_add_i32 s3, s3, 1
	s_mov_b64 s[56:57], -1
	s_waitcnt vmcnt(0)
	v_cmp_ge_u32_e32 vcc, v0, v16
	s_orn2_b64 s[54:55], vcc, exec
	s_branch .LBB0_209

; __device__ __forceinline__ unsigned xb_ld(unsigned* p)              { return __hip_atomic_load(p, __ATOMIC_RELAXED, __HIP_MEMORY_SCOPE_AGENT); }
; __device__ __forceinline__ unsigned xb_add(unsigned* p, unsigned v) { return __hip_atomic_fetch_add(p, v, __ATOMIC_RELAXED, __HIP_MEMORY_SCOPE_AGENT); }
; #define XB_SPIN(cond, bar) do { unsigned _sp = 0; while (cond) { __builtin_amdgcn_s_sleep(1); \
;     if ((++_sp & 255u) == 0u) { if (xb_ld(&(bar)[XB_TMO])) break; if (_sp > XB_SPIN_CAP) { atomicAdd(&(bar)[XB_TMO], 1u); break; } } } } while (0)
; __device__ __forceinline__ void xcd_barrier(const XcdBarrier& b) {
;     ...
;             const unsigned og = xb_add(&bar[XB_TOP], 1u);
;             const unsigned tg = og / nx;
;             if (og + 1u == (tg + 1u) * nx) xb_add(&bar[XB_TOPGEN], 1u);
;             else XB_SPIN(xb_ld(&bar[XB_TOPGEN]) == tg, bar);
.LBB0_223:
	s_or_b64 exec, exec, s[12:13]
	s_waitcnt vmcnt(0)
	v_readfirstlane_b32 s3, v2
	v_cvt_f32_u32_e32 v2, v0
	v_sub_u32_e32 v3, 0, v0
	v_add_u32_e32 v1, s3, v1
	s_add_u32 s10, s6, 0x2e803500
	v_rcp_iflag_f32_e32 v2, v2
	s_addc_u32 s11, s7, 0
	s_mov_b64 s[14:15], 0
	v_mul_f32_e32 v2, 0x4f7ffffe, v2
	v_cvt_u32_f32_e32 v2, v2
	v_mul_lo_u32 v3, v3, v2
	v_mul_hi_u32 v3, v2, v3
	v_add_u32_e32 v2, v2, v3
	v_mul_hi_u32 v2, v1, v2
	v_mul_lo_u32 v3, v2, v0
	v_sub_u32_e32 v3, v1, v3
	v_cmp_ge_u32_e32 vcc, v3, v0
	v_add_u32_e32 v4, 1, v2
	v_add_u32_e32 v1, 1, v1
	v_cndmask_b32_e32 v2, v2, v4, vcc
	v_sub_u32_e32 v4, v3, v0
	v_cndmask_b32_e32 v3, v3, v4, vcc
	v_cmp_ge_u32_e32 vcc, v3, v0
	v_add_u32_e32 v3, 1, v2
	s_nop 0
	v_cndmask_b32_e32 v2, v2, v3, vcc
	v_mul_lo_u32 v3, v0, v2
	v_add_u32_e32 v0, v3, v0
	v_mov_b32_e32 v16, v0
	v_cmp_ne_u32_e32 vcc, v1, v0
	v_mov_b64_e32 v[0:1], s[10:11]
	s_and_saveexec_b64 s[12:13], vcc
	s_cbranch_execz .LBB0_235
	global_load_dword v0, v97, s[10:11] offset:-256 sc1
	s_mov_b64 s[34:35], 0
	s_waitcnt vmcnt(0)
	v_cmp_lt_u32_e32 vcc, v0, v16
	s_and_saveexec_b64 s[16:17], vcc
	s_cbranch_execz .LBB0_234
	s_add_u32 s14, s6, 0x2e800200
	s_addc_u32 s15, s7, 0
	s_mov_b32 s3, 1
	s_mov_b64 s[6:7], 0
	s_branch .LBB0_227

; __device__ __forceinline__ unsigned xb_ld(unsigned* p)              { return __hip_atomic_load(p, __ATOMIC_RELAXED, __HIP_MEMORY_SCOPE_AGENT); }
; __device__ __forceinline__ unsigned xb_add(unsigned* p, unsigned v) { return __hip_atomic_fetch_add(p, v, __ATOMIC_RELAXED, __HIP_MEMORY_SCOPE_AGENT); }
; #define XB_SPIN(cond, bar) do { unsigned _sp = 0; while (cond) { __builtin_amdgcn_s_sleep(1); \
;     if ((++_sp & 255u) == 0u) { if (xb_ld(&(bar)[XB_TMO])) break; if (_sp > XB_SPIN_CAP) { atomicAdd(&(bar)[XB_TMO], 1u); break; } } } } while (0)
; __device__ __forceinline__ void xcd_barrier(const XcdBarrier& b) {
;     ...
;             else XB_SPIN(xb_ld(&bar[XB_TOPGEN]) == tg, bar);
;             __builtin_amdgcn_fence(__ATOMIC_ACQUIRE, "agent");
;             xb_add(&bar[XB_XGEN(b.x)], 1u);
;             asm volatile("s_waitcnt vmcnt(0)" ::: "memory");
;         } else {
;             XB_SPIN(xb_ld(&bar[XB_XGEN(b.x)]) == gen, bar);
.LBB0_231:
	global_load_dword v0, v97, s[10:11] offset:-256 sc1
	s_add_i32 s3, s3, 1
	s_mov_b64 s[54:55], -1
	s_waitcnt vmcnt(0)
	v_cmp_ge_u32_e32 vcc, v0, v16
	s_orn2_b64 s[52:53], vcc, exec
	s_branch .LBB0_226

; __device__ __forceinline__ unsigned xb_ld(unsigned* p)              { return __hip_atomic_load(p, __ATOMIC_RELAXED, __HIP_MEMORY_SCOPE_AGENT); }
; __device__ __forceinline__ unsigned xb_add(unsigned* p, unsigned v) { return __hip_atomic_fetch_add(p, v, __ATOMIC_RELAXED, __HIP_MEMORY_SCOPE_AGENT); }
; #define XB_SPIN(cond, bar) do { unsigned _sp = 0; while (cond) { __builtin_amdgcn_s_sleep(1); \
;     if ((++_sp & 255u) == 0u) { if (xb_ld(&(bar)[XB_TMO])) break; if (_sp > XB_SPIN_CAP) { atomicAdd(&(bar)[XB_TMO], 1u); break; } } } } while (0)
; __device__ __forceinline__ void xcd_barrier(const XcdBarrier& b) {
;     ...
;         const unsigned old = xb_add(&bar[XB_XSUB(b.x)], 1u);
;         const unsigned gen = old / nloc;
;         if (old + 1u == (gen + 1u) * nloc) {
;             __builtin_amdgcn_fence(__ATOMIC_RELEASE, "agent");
;             asm volatile("s_waitcnt vmcnt(0)" ::: "memory");
;             const unsigned og = xb_add(&bar[XB_TOP], 1u);
;             const unsigned tg = og / nx;
;             if (og + 1u == (tg + 1u) * nx) xb_add(&bar[XB_TOPGEN], 1u);
;             else XB_SPIN(xb_ld(&bar[XB_TOPGEN]) == tg, bar);
;             __builtin_amdgcn_fence(__ATOMIC_ACQUIRE, "agent");
;             xb_add(&bar[XB_XGEN(b.x)], 1u);
;             asm volatile("s_waitcnt vmcnt(0)" ::: "memory");
;         } else {
;             XB_SPIN(xb_ld(&bar[XB_XGEN(b.x)]) == gen, bar);
.LBB0_306:
	s_or_b64 exec, exec, s[12:13]
	v_cvt_f32_u32_e32 v4, v2
	s_waitcnt vmcnt(0)
	v_readfirstlane_b32 s2, v3
	v_sub_u32_e32 v3, 0, v2
	v_rcp_iflag_f32_e32 v4, v4
	v_add_u32_e32 v5, s2, v1
	v_mul_f32_e32 v4, 0x4f7ffffe, v4
	v_cvt_u32_f32_e32 v4, v4
	v_mul_lo_u32 v1, v3, v4
	v_mul_hi_u32 v1, v4, v1
	v_add_u32_e32 v1, v4, v1
	v_mul_hi_u32 v1, v5, v1
	v_mul_lo_u32 v3, v1, v2
	v_sub_u32_e32 v3, v5, v3
	v_add_u32_e32 v4, 1, v1
	v_cmp_ge_u32_e32 vcc, v3, v2
	s_nop 1
	v_cndmask_b32_e32 v1, v1, v4, vcc
	v_sub_u32_e32 v4, v3, v2
	v_cndmask_b32_e32 v3, v3, v4, vcc
	v_add_u32_e32 v4, 1, v1
	v_cmp_ge_u32_e32 vcc, v3, v2
	v_add_u32_e32 v3, 1, v5
	s_nop 0
	v_cndmask_b32_e32 v1, v1, v4, vcc
	v_mul_lo_u32 v4, v2, v1
	v_add_u32_e32 v2, v4, v2
	v_cmp_ne_u32_e32 vcc, v3, v2
	s_and_saveexec_b64 s[2:3], vcc
	s_xor_b64 s[10:11], exec, s[2:3]
	s_cbranch_execz .LBB0_320
	s_waitcnt lgkmcnt(0)
	v_add_u32_e32 v16, 1, v1
	v_mul_lo_u32 v16, v16, v0
	s_add_u32 s16, s6, 0x2e803400
	s_addc_u32 s17, s7, 0
	global_load_dword v0, v97, s[16:17] sc1
	s_waitcnt vmcnt(0)
	v_cmp_lt_u32_e32 vcc, v0, v16
	s_and_saveexec_b64 s[12:13], vcc
	s_cbranch_execz .LBB0_319
	s_add_u32 s14, s6, 0x2e800200
	s_addc_u32 s15, s7, 0
	s_mov_b32 s2, 1
	s_mov_b64 s[34:35], 0
	s_branch .LBB0_310

; __device__ __forceinline__ unsigned xb_ld(unsigned* p)              { return __hip_atomic_load(p, __ATOMIC_RELAXED, __HIP_MEMORY_SCOPE_AGENT); }
; __device__ __forceinline__ unsigned xb_add(unsigned* p, unsigned v) { return __hip_atomic_fetch_add(p, v, __ATOMIC_RELAXED, __HIP_MEMORY_SCOPE_AGENT); }
; #define XB_SPIN(cond, bar) do { unsigned _sp = 0; while (cond) { __builtin_amdgcn_s_sleep(1); \
;     if ((++_sp & 255u) == 0u) { if (xb_ld(&(bar)[XB_TMO])) break; if (_sp > XB_SPIN_CAP) { atomicAdd(&(bar)[XB_TMO], 1u); break; } } } } while (0)
; __device__ __forceinline__ void xcd_barrier(const XcdBarrier& b) {
;     ...
;             else XB_SPIN(xb_ld(&bar[XB_TOPGEN]) == tg, bar);
;             __builtin_amdgcn_fence(__ATOMIC_ACQUIRE, "agent");
;             xb_add(&bar[XB_XGEN(b.x)], 1u);
;             asm volatile("s_waitcnt vmcnt(0)" ::: "memory");
;         } else {
;             XB_SPIN(xb_ld(&bar[XB_XGEN(b.x)]) == gen, bar);
.LBB0_314:
	global_load_dword v0, v97, s[16:17] sc1
	s_add_i32 s2, s2, 1
	s_mov_b64 s[56:57], -1
	s_waitcnt vmcnt(0)
	v_cmp_ge_u32_e32 vcc, v0, v16
	s_orn2_b64 s[54:55], vcc, exec
	s_branch .LBB0_309

; __device__ __forceinline__ unsigned xb_ld(unsigned* p)              { return __hip_atomic_load(p, __ATOMIC_RELAXED, __HIP_MEMORY_SCOPE_AGENT); }
; __device__ __forceinline__ unsigned xb_add(unsigned* p, unsigned v) { return __hip_atomic_fetch_add(p, v, __ATOMIC_RELAXED, __HIP_MEMORY_SCOPE_AGENT); }
; #define XB_SPIN(cond, bar) do { unsigned _sp = 0; while (cond) { __builtin_amdgcn_s_sleep(1); \
;     if ((++_sp & 255u) == 0u) { if (xb_ld(&(bar)[XB_TMO])) break; if (_sp > XB_SPIN_CAP) { atomicAdd(&(bar)[XB_TMO], 1u); break; } } } } while (0)
; __device__ __forceinline__ void xcd_barrier(const XcdBarrier& b) {
;     ...
;             const unsigned og = xb_add(&bar[XB_TOP], 1u);
;             const unsigned tg = og / nx;
;             if (og + 1u == (tg + 1u) * nx) xb_add(&bar[XB_TOPGEN], 1u);
;             else XB_SPIN(xb_ld(&bar[XB_TOPGEN]) == tg, bar);
.LBB0_323:
	s_or_b64 exec, exec, s[12:13]
	s_waitcnt vmcnt(0)
	v_readfirstlane_b32 s2, v2
	v_cvt_f32_u32_e32 v2, v0
	v_sub_u32_e32 v3, 0, v0
	v_add_u32_e32 v1, s2, v1
	s_add_u32 s10, s6, 0x2e803500
	v_rcp_iflag_f32_e32 v2, v2
	s_addc_u32 s11, s7, 0
	s_mov_b64 s[14:15], 0
	v_mul_f32_e32 v2, 0x4f7ffffe, v2
	v_cvt_u32_f32_e32 v2, v2
	v_mul_lo_u32 v3, v3, v2
	v_mul_hi_u32 v3, v2, v3
	v_add_u32_e32 v2, v2, v3
	v_mul_hi_u32 v2, v1, v2
	v_mul_lo_u32 v3, v2, v0
	v_sub_u32_e32 v3, v1, v3
	v_cmp_ge_u32_e32 vcc, v3, v0
	v_add_u32_e32 v4, 1, v2
	v_add_u32_e32 v1, 1, v1
	v_cndmask_b32_e32 v2, v2, v4, vcc
	v_sub_u32_e32 v4, v3, v0
	v_cndmask_b32_e32 v3, v3, v4, vcc
	v_cmp_ge_u32_e32 vcc, v3, v0
	v_add_u32_e32 v3, 1, v2
	s_nop 0
	v_cndmask_b32_e32 v2, v2, v3, vcc
	v_mul_lo_u32 v3, v0, v2
	v_add_u32_e32 v0, v3, v0
	v_mov_b32_e32 v16, v0
	v_cmp_ne_u32_e32 vcc, v1, v0
	v_mov_b64_e32 v[0:1], s[10:11]
	s_and_saveexec_b64 s[12:13], vcc
	s_cbranch_execz .LBB0_335
	global_load_dword v0, v97, s[10:11] offset:-256 sc1
	s_mov_b64 s[34:35], 0
	s_waitcnt vmcnt(0)
	v_cmp_lt_u32_e32 vcc, v0, v16
	s_and_saveexec_b64 s[16:17], vcc
	s_cbranch_execz .LBB0_334
	s_add_u32 s14, s6, 0x2e800200
	s_addc_u32 s15, s7, 0
	s_mov_b32 s2, 1
	s_mov_b64 s[6:7], 0
	s_branch .LBB0_327

; __device__ __forceinline__ unsigned xb_ld(unsigned* p)              { return __hip_atomic_load(p, __ATOMIC_RELAXED, __HIP_MEMORY_SCOPE_AGENT); }
; __device__ __forceinline__ unsigned xb_add(unsigned* p, unsigned v) { return __hip_atomic_fetch_add(p, v, __ATOMIC_RELAXED, __HIP_MEMORY_SCOPE_AGENT); }
; #define XB_SPIN(cond, bar) do { unsigned _sp = 0; while (cond) { __builtin_amdgcn_s_sleep(1); \
;     if ((++_sp & 255u) == 0u) { if (xb_ld(&(bar)[XB_TMO])) break; if (_sp > XB_SPIN_CAP) { atomicAdd(&(bar)[XB_TMO], 1u); break; } } } } while (0)
; __device__ __forceinline__ void xcd_barrier(const XcdBarrier& b) {
;     ...
;             else XB_SPIN(xb_ld(&bar[XB_TOPGEN]) == tg, bar);
;             __builtin_amdgcn_fence(__ATOMIC_ACQUIRE, "agent");
;             xb_add(&bar[XB_XGEN(b.x)], 1u);
;             asm volatile("s_waitcnt vmcnt(0)" ::: "memory");
;         } else {
;             XB_SPIN(xb_ld(&bar[XB_XGEN(b.x)]) == gen, bar);
.LBB0_331:
	global_load_dword v0, v97, s[10:11] offset:-256 sc1
	s_add_i32 s2, s2, 1
	s_mov_b64 s[54:55], -1
	s_waitcnt vmcnt(0)
	v_cmp_ge_u32_e32 vcc, v0, v16
	s_orn2_b64 s[52:53], vcc, exec
	s_branch .LBB0_326

; __device__ __forceinline__ unsigned xb_ld(unsigned* p)              { return __hip_atomic_load(p, __ATOMIC_RELAXED, __HIP_MEMORY_SCOPE_AGENT); }
; __device__ __forceinline__ unsigned xb_add(unsigned* p, unsigned v) { return __hip_atomic_fetch_add(p, v, __ATOMIC_RELAXED, __HIP_MEMORY_SCOPE_AGENT); }
; #define XB_SPIN(cond, bar) do { unsigned _sp = 0; while (cond) { __builtin_amdgcn_s_sleep(1); \
;     if ((++_sp & 255u) == 0u) { if (xb_ld(&(bar)[XB_TMO])) break; if (_sp > XB_SPIN_CAP) { atomicAdd(&(bar)[XB_TMO], 1u); break; } } } } while (0)
; __device__ __forceinline__ void xcd_barrier(const XcdBarrier& b) {
;     ...
;         const unsigned old = xb_add(&bar[XB_XSUB(b.x)], 1u);
;         const unsigned gen = old / nloc;
;         if (old + 1u == (gen + 1u) * nloc) {
;             __builtin_amdgcn_fence(__ATOMIC_RELEASE, "agent");
;             asm volatile("s_waitcnt vmcnt(0)" ::: "memory");
;             const unsigned og = xb_add(&bar[XB_TOP], 1u);
;             const unsigned tg = og / nx;
;             if (og + 1u == (tg + 1u) * nx) xb_add(&bar[XB_TOPGEN], 1u);
;             else XB_SPIN(xb_ld(&bar[XB_TOPGEN]) == tg, bar);
;             __builtin_amdgcn_fence(__ATOMIC_ACQUIRE, "agent");
;             xb_add(&bar[XB_XGEN(b.x)], 1u);
;             asm volatile("s_waitcnt vmcnt(0)" ::: "memory");
;         } else {
;             XB_SPIN(xb_ld(&bar[XB_XGEN(b.x)]) == gen, bar);
.LBB0_672:
	s_or_b64 exec, exec, s[14:15]
	v_cvt_f32_u32_e32 v4, v2
	s_waitcnt vmcnt(0)
	v_readfirstlane_b32 s3, v3
	v_sub_u32_e32 v3, 0, v2
	v_rcp_iflag_f32_e32 v4, v4
	v_add_u32_e32 v5, s3, v1
	v_mul_f32_e32 v4, 0x4f7ffffe, v4
	v_cvt_u32_f32_e32 v4, v4
	v_mul_lo_u32 v1, v3, v4
	v_mul_hi_u32 v1, v4, v1
	v_add_u32_e32 v1, v4, v1
	v_mul_hi_u32 v1, v5, v1
	v_mul_lo_u32 v3, v1, v2
	v_sub_u32_e32 v3, v5, v3
	v_add_u32_e32 v4, 1, v1
	v_cmp_ge_u32_e32 vcc, v3, v2
	s_nop 1
	v_cndmask_b32_e32 v1, v1, v4, vcc
	v_sub_u32_e32 v4, v3, v2
	v_cndmask_b32_e32 v3, v3, v4, vcc
	v_add_u32_e32 v4, 1, v1
	v_cmp_ge_u32_e32 vcc, v3, v2
	v_add_u32_e32 v3, 1, v5
	s_nop 0
	v_cndmask_b32_e32 v1, v1, v4, vcc
	v_mul_lo_u32 v4, v2, v1
	v_add_u32_e32 v2, v4, v2
	v_cmp_ne_u32_e32 vcc, v3, v2
	s_and_saveexec_b64 s[10:11], vcc
	s_xor_b64 s[10:11], exec, s[10:11]
	s_cbranch_execz .LBB0_703
	s_waitcnt lgkmcnt(0)
	v_add_u32_e32 v16, 1, v1
	v_mul_lo_u32 v16, v16, v0
	s_add_u32 s34, s6, 0x2e803400
	s_addc_u32 s35, s7, 0
	global_load_dword v0, v97, s[34:35] sc1
	s_waitcnt vmcnt(0)
	v_cmp_lt_u32_e32 vcc, v0, v16
	s_and_saveexec_b64 s[14:15], vcc
	s_cbranch_execz .LBB0_702
	s_add_u32 s16, s6, 0x2e800200
	s_addc_u32 s17, s7, 0
	s_mov_b32 s3, 1
	s_mov_b64 s[52:53], 0
	s_branch .LBB0_676

; __device__ __forceinline__ unsigned xb_ld(unsigned* p)              { return __hip_atomic_load(p, __ATOMIC_RELAXED, __HIP_MEMORY_SCOPE_AGENT); }
; __device__ __forceinline__ unsigned xb_add(unsigned* p, unsigned v) { return __hip_atomic_fetch_add(p, v, __ATOMIC_RELAXED, __HIP_MEMORY_SCOPE_AGENT); }
; #define XB_SPIN(cond, bar) do { unsigned _sp = 0; while (cond) { __builtin_amdgcn_s_sleep(1); \
;     if ((++_sp & 255u) == 0u) { if (xb_ld(&(bar)[XB_TMO])) break; if (_sp > XB_SPIN_CAP) { atomicAdd(&(bar)[XB_TMO], 1u); break; } } } } while (0)
; __device__ __forceinline__ void xcd_barrier(const XcdBarrier& b) {
;     ...
;             else XB_SPIN(xb_ld(&bar[XB_TOPGEN]) == tg, bar);
;             __builtin_amdgcn_fence(__ATOMIC_ACQUIRE, "agent");
;             xb_add(&bar[XB_XGEN(b.x)], 1u);
;             asm volatile("s_waitcnt vmcnt(0)" ::: "memory");
;         } else {
;             XB_SPIN(xb_ld(&bar[XB_XGEN(b.x)]) == gen, bar);
.LBB0_680:
	global_load_dword v0, v97, s[34:35] sc1
	s_add_i32 s3, s3, 1
	s_mov_b64 s[60:61], -1
	s_waitcnt vmcnt(0)
	v_cmp_ge_u32_e32 vcc, v0, v16
	s_orn2_b64 s[56:57], vcc, exec
	s_branch .LBB0_675

; __device__ __forceinline__ unsigned xb_ld(unsigned* p)              { return __hip_atomic_load(p, __ATOMIC_RELAXED, __HIP_MEMORY_SCOPE_AGENT); }
; __device__ __forceinline__ unsigned xb_add(unsigned* p, unsigned v) { return __hip_atomic_fetch_add(p, v, __ATOMIC_RELAXED, __HIP_MEMORY_SCOPE_AGENT); }
; #define XB_SPIN(cond, bar) do { unsigned _sp = 0; while (cond) { __builtin_amdgcn_s_sleep(1); \
;     if ((++_sp & 255u) == 0u) { if (xb_ld(&(bar)[XB_TMO])) break; if (_sp > XB_SPIN_CAP) { atomicAdd(&(bar)[XB_TMO], 1u); break; } } } } while (0)
; __device__ __forceinline__ void xcd_barrier(const XcdBarrier& b) {
;     ...
;             const unsigned og = xb_add(&bar[XB_TOP], 1u);
;             const unsigned tg = og / nx;
;             if (og + 1u == (tg + 1u) * nx) xb_add(&bar[XB_TOPGEN], 1u);
;             else XB_SPIN(xb_ld(&bar[XB_TOPGEN]) == tg, bar);
.LBB0_706:
	s_or_b64 exec, exec, s[14:15]
	v_cvt_f32_u32_e32 v3, v0
	s_waitcnt vmcnt(0)
	v_readfirstlane_b32 s3, v2
	s_add_u32 s10, s6, 0x2e803500
	s_addc_u32 s11, s7, 0
	v_rcp_iflag_f32_e32 v3, v3
	v_add_u32_e32 v1, s3, v1
	v_add_u32_e32 v4, 1, v1
	s_mov_b64 s[16:17], 0
	v_mul_f32_e32 v2, 0x4f7ffffe, v3
	v_cvt_u32_f32_e32 v2, v2
	v_sub_u32_e32 v3, 0, v0
	v_mul_lo_u32 v3, v3, v2
	v_mul_hi_u32 v3, v2, v3
	v_add_u32_e32 v2, v2, v3
	v_mul_hi_u32 v2, v1, v2
	v_mul_lo_u32 v3, v2, v0
	v_sub_u32_e32 v1, v1, v3
	v_add_u32_e32 v5, 1, v2
	v_cmp_ge_u32_e32 vcc, v1, v0
	v_sub_u32_e32 v3, v1, v0
	s_nop 0
	v_cndmask_b32_e32 v2, v2, v5, vcc
	v_cndmask_b32_e32 v1, v1, v3, vcc
	v_add_u32_e32 v3, 1, v2
	v_cmp_ge_u32_e32 vcc, v1, v0
	s_nop 1
	v_cndmask_b32_e32 v2, v2, v3, vcc
	v_mul_lo_u32 v1, v0, v2
	v_add_u32_e32 v0, v1, v0
	v_mov_b32_e32 v16, v0
	v_cmp_ne_u32_e32 vcc, v4, v0
	v_mov_b64_e32 v[0:1], s[10:11]
	s_and_saveexec_b64 s[14:15], vcc
	s_cbranch_execz .LBB0_735
	global_load_dword v0, v97, s[10:11] offset:-256 sc1
	s_mov_b64 s[52:53], 0
	s_waitcnt vmcnt(0)
	v_cmp_lt_u32_e32 vcc, v0, v16
	s_and_saveexec_b64 s[34:35], vcc
	s_cbranch_execz .LBB0_734
	s_add_u32 s16, s6, 0x2e800200
	s_addc_u32 s17, s7, 0
	s_mov_b32 s3, 1
	s_mov_b64 s[6:7], 0
	s_branch .LBB0_710

; __device__ __forceinline__ unsigned xb_ld(unsigned* p)              { return __hip_atomic_load(p, __ATOMIC_RELAXED, __HIP_MEMORY_SCOPE_AGENT); }
; #define XB_SPIN(cond, bar) do { unsigned _sp = 0; while (cond) { __builtin_amdgcn_s_sleep(1); \
;     if ((++_sp & 255u) == 0u) { if (xb_ld(&(bar)[XB_TMO])) break; if (_sp > XB_SPIN_CAP) { atomicAdd(&(bar)[XB_TMO], 1u); break; } } } } while (0)
; __device__ __forceinline__ void xcd_barrier(const XcdBarrier& b) {
;     ...
;             else XB_SPIN(xb_ld(&bar[XB_TOPGEN]) == tg, bar);
.LBB0_714:
	global_load_dword v0, v97, s[10:11] offset:-256 sc1
	s_add_i32 s3, s3, 1
	s_mov_b64 s[56:57], -1
	s_waitcnt vmcnt(0)
	v_cmp_ge_u32_e32 vcc, v0, v16
	s_orn2_b64 s[54:55], vcc, exec
	s_branch .LBB0_709
